# P3 band-edge tiles: bias pairs read straight into place and first QK MFMAs write the score accumulators directly (no register copies)
# speedup vs baseline: 1.0455x; 1.0005x over previous
.LBB0_552:
	v_cndmask_b32_e64 v32, 0, 1, s[38:39]
	v_cmp_ne_u32_e64 s[4:5], 1, v32
	s_andn2_b64 vcc, exec, s[38:39]
	s_cbranch_vccnz .LBB0_570
	s_add_i32 s49, s71, s48
	s_cmp_gt_i32 s49, s73
	s_cselect_b64 s[46:47], -1, 0
	s_cmp_lt_i32 s49, s74
	s_cselect_b64 s[78:79], -1, 0
	s_or_b64 s[46:47], s[46:47], s[78:79]
	s_and_b64 vcc, exec, s[46:47]
	s_cbranch_vccnz .LBB0_570
	s_add_i32 s46, s76, s72
	s_cmp_gt_i32 s46, 2
	s_cselect_b64 s[46:47], -1, 0
	s_and_b64 vcc, exec, s[46:47]
	s_cbranch_vccnz .LBB0_556
	ds_read2_b32 v[0:1], v191 offset0:59 offset1:58
	ds_read2_b32 v[2:3], v191 offset0:57 offset1:56
	ds_read2_b32 v[4:5], v191 offset0:51 offset1:50
	ds_read2_b32 v[6:7], v191 offset0:49 offset1:48
	ds_read2_b32 v[8:9], v191 offset0:43 offset1:42
	ds_read2_b32 v[10:11], v191 offset0:41 offset1:40
	ds_read2_b32 v[12:13], v191 offset0:35 offset1:34
	ds_read2_b32 v[14:15], v191 offset0:33 offset1:32
	s_waitcnt lgkmcnt(7)
	v_pk_add_f32 v[0:1], v[0:1], v[78:79] op_sel_hi:[1,0] neg_lo:[0,1] neg_hi:[0,1]
	ds_read2_b32 v[16:17], v191 offset0:27 offset1:26
	s_waitcnt lgkmcnt(7)
	v_pk_add_f32 v[2:3], v[2:3], v[78:79] op_sel_hi:[1,0] neg_lo:[0,1] neg_hi:[0,1]
	ds_read2_b32 v[18:19], v191 offset0:25 offset1:24
	s_waitcnt lgkmcnt(7)
	v_pk_add_f32 v[4:5], v[4:5], v[78:79] op_sel_hi:[1,0] neg_lo:[0,1] neg_hi:[0,1]
	ds_read2_b32 v[20:21], v191 offset0:19 offset1:18
	s_waitcnt lgkmcnt(7)
	v_pk_add_f32 v[6:7], v[6:7], v[78:79] op_sel_hi:[1,0] neg_lo:[0,1] neg_hi:[0,1]
	ds_read2_b32 v[22:23], v191 offset0:17 offset1:16
	s_waitcnt lgkmcnt(7)
	v_pk_add_f32 v[8:9], v[8:9], v[78:79] op_sel_hi:[1,0] neg_lo:[0,1] neg_hi:[0,1]
	ds_read2_b32 v[24:25], v191 offset0:11 offset1:10
	s_waitcnt lgkmcnt(7)
	v_pk_add_f32 v[10:11], v[10:11], v[78:79] op_sel_hi:[1,0] neg_lo:[0,1] neg_hi:[0,1]
	ds_read2_b32 v[26:27], v191 offset0:9 offset1:8
	s_waitcnt lgkmcnt(7)
	v_pk_add_f32 v[12:13], v[12:13], v[78:79] op_sel_hi:[1,0] neg_lo:[0,1] neg_hi:[0,1]
	ds_read2_b32 v[28:29], v191 offset0:3 offset1:2
	s_waitcnt lgkmcnt(7)
	v_pk_add_f32 v[14:15], v[14:15], v[78:79] op_sel_hi:[1,0] neg_lo:[0,1] neg_hi:[0,1]
	ds_read2_b32 v[30:31], v191 offset0:1
	s_waitcnt lgkmcnt(7)
	v_pk_add_f32 v[16:17], v[16:17], v[78:79] op_sel_hi:[1,0] neg_lo:[0,1] neg_hi:[0,1]
	s_waitcnt lgkmcnt(6)
	v_pk_add_f32 v[18:19], v[18:19], v[78:79] op_sel_hi:[1,0] neg_lo:[0,1] neg_hi:[0,1]
	s_waitcnt lgkmcnt(5)
	v_pk_add_f32 v[20:21], v[20:21], v[78:79] op_sel_hi:[1,0] neg_lo:[0,1] neg_hi:[0,1]
	s_waitcnt lgkmcnt(4)
	v_pk_add_f32 v[22:23], v[22:23], v[78:79] op_sel_hi:[1,0] neg_lo:[0,1] neg_hi:[0,1]
	s_waitcnt lgkmcnt(3)
	v_pk_add_f32 v[24:25], v[24:25], v[78:79] op_sel_hi:[1,0] neg_lo:[0,1] neg_hi:[0,1]
	s_waitcnt lgkmcnt(2)
	v_pk_add_f32 v[26:27], v[26:27], v[78:79] op_sel_hi:[1,0] neg_lo:[0,1] neg_hi:[0,1]
	s_waitcnt lgkmcnt(1)
	v_pk_add_f32 v[28:29], v[28:29], v[78:79] op_sel_hi:[1,0] neg_lo:[0,1] neg_hi:[0,1]
	s_waitcnt lgkmcnt(0)
	v_pk_add_f32 v[30:31], v[30:31], v[78:79] op_sel_hi:[1,0] neg_lo:[0,1] neg_hi:[0,1]

.LBB0_558:
	s_andn2_b64 vcc, exec, s[48:49]
	s_cbranch_vccnz .LBB0_560
	s_waitcnt lgkmcnt(7)
	v_mfma_f32_32x32x16_bf16 v[48:63], v[164:167], v[140:143], v[0:15]
	s_waitcnt lgkmcnt(3)
	v_mfma_f32_32x32x16_bf16 v[32:47], v[160:163], v[140:143], v[16:31]
